# prologue: per-matrix rotation of the wave index so each wave gets 8-11 weight-transpose items instead of 0-24
# baseline (speedup 1.0000x reference)
; #define LAS __attribute__((address_space(3)))
; #define PH_BEGIN if (ph >= lo && ph < hi_) {
; __global__ void __launch_bounds__(512, 2) fwd_kernel(Args a) {
;     ...
;     const int G = (int)gridDim.x, gw = (int)blockIdx.x * 8 + wave, NGW = G * 8;
;     ...
;     PH_BEGIN
;     {
;         LAS float* scr = (LAS float*)(lds + wave * 8448);
;         for (int l = 0; l < 4; ++l) {
;             transpose_matrix(a.f_wg + (size_t)l * DM * FF, DM, FF, Wgu + (size_t)l * NGU * DM, 1, scr, gw, NGW, lane, a.norm_ffn_g + l * DM);
;             transpose_matrix(a.f_wu + (size_t)l * DM * FF, DM, FF, Wgu + (size_t)l * NGU * DM, 2, scr, gw, NGW, lane, a.norm_ffn_g + l * DM);
;             transpose_matrix(a.f_wd + (size_t)l * FF * DM, FF, DM, Wd + (size_t)l * DM * FF, 0, scr, gw, NGW, lane);
;         }
;         transpose_matrix(a.w_qkv, DM, NQKV, Wqkv, 0, scr, gw, NGW, lane, a.norm_mix_g + 1 * DM);
;         transpose_matrix(a.w_o, DM, DM, Wo, 0, scr, gw, NGW, lane);
.LBB0_15:
	s_load_dwordx16 s[36:51], s[0:1], 0x40
	v_writelane_b32 v247, s14, 24
	s_add_u32 s82, s76, 0x1d400000
	s_addc_u32 s83, s77, 0
	v_writelane_b32 v247, s15, 25
	s_waitcnt lgkmcnt(0)
	v_writelane_b32 v247, s36, 26
	s_load_dwordx16 s[4:19], s[0:1], 0x80
	s_add_u32 s86, s76, 0x1d604000
	v_writelane_b32 v247, s37, 27
	v_writelane_b32 v247, s38, 28
	v_writelane_b32 v247, s39, 29
	v_writelane_b32 v247, s40, 30
	v_writelane_b32 v247, s41, 31
	v_writelane_b32 v247, s42, 32
	v_writelane_b32 v247, s43, 33
	v_writelane_b32 v247, s44, 34
	v_writelane_b32 v247, s45, 35
	v_writelane_b32 v247, s46, 36
	v_writelane_b32 v247, s47, 37
	v_writelane_b32 v247, s48, 38
	v_writelane_b32 v247, s49, 39
	v_writelane_b32 v247, s50, 40
	v_writelane_b32 v247, s51, 41
	s_waitcnt lgkmcnt(0)
	v_writelane_b32 v247, s4, 42
	s_addc_u32 s87, s77, 0
	s_add_u32 s0, s76, 0x1cd00000
	v_writelane_b32 v247, s5, 43
	v_writelane_b32 v247, s6, 44
	v_writelane_b32 v247, s7, 45
	v_writelane_b32 v247, s8, 46
	v_writelane_b32 v247, s9, 47
	v_writelane_b32 v247, s10, 48
	v_writelane_b32 v247, s11, 49
	v_writelane_b32 v247, s12, 50
	v_writelane_b32 v247, s13, 51
	v_writelane_b32 v247, s14, 52
	v_writelane_b32 v247, s15, 53
	v_writelane_b32 v247, s16, 54
	s_addc_u32 s1, s77, 0
	v_writelane_b32 v247, s17, 55
	s_add_u32 s96, s76, 0x1d100000
	v_writelane_b32 v247, s18, 56
	s_addc_u32 s97, s77, 0
	v_writelane_b32 v247, s19, 57
	s_add_u32 s12, s76, 0x1d300000
	s_addc_u32 s13, s77, 0
	s_lshl_b32 s33, s88, 3
	s_add_u32 s80, s76, 0x8100000
	s_addc_u32 s81, s77, 0
	s_add_u32 s84, s76, 0x18300000
	v_writelane_b32 v247, s0, 58
	s_addc_u32 s85, s77, 0
	v_and_b32_e32 v164, 63, v163
	v_writelane_b32 v247, s1, 59
	s_add_u32 s0, s76, 0x1af00000
	s_addc_u32 s1, s77, 0
	s_add_u32 s94, s76, 0x1c500000
	v_writelane_b32 v247, s0, 60
	s_addc_u32 s95, s77, 0
	v_lshrrev_b32_e32 v165, 6, v163
	v_writelane_b32 v247, s1, 61
	s_add_u32 s0, s76, 0x1cb00000
	s_addc_u32 s1, s77, 0
	s_cmp_lt_i32 s78, 1
	s_cselect_b64 s[8:9], -1, 0
	s_cmp_gt_i32 s79, 0
	s_cselect_b64 s[4:5], -1, 0
	v_writelane_b32 v247, s0, 62
	s_and_b64 s[4:5], s[8:9], s[4:5]
	v_mul_u32_u24_e32 v162, s88, v165
	v_add_u32_e32 v162, s2, v162
	v_mov_b32_e32 v255, v162
	v_writelane_b32 v247, s1, 63
	s_mov_b32 s1, 0
	s_andn2_b64 vcc, exec, s[4:5]
	v_lshrrev_b32_e32 v169, 5, v164
	v_and_b32_e32 v168, 31, v163
	s_cbranch_vccnz .LBB0_61
	s_movk_i32 s0, 0x2100
	v_mad_u32_u24 v2, v165, s0, 0
	v_lshlrev_b32_e32 v10, 2, v168
	v_mul_u32_u24_e32 v3, 0x84, v169
	v_readlane_b32 s16, v247, 8
	v_add3_u32 v13, v2, v10, v3
	v_lshlrev_b32_e32 v3, 3, v163
	v_readlane_b32 s36, v247, 0
	v_readlane_b32 s22, v247, 14
	v_readlane_b32 s23, v247, 15
	v_lshrrev_b32_e32 v60, 3, v164
	v_and_b32_e32 v4, 56, v3
	v_mov_b32_e32 v11, 0
	v_readlane_b32 s37, v247, 1
	v_readlane_b32 s38, v247, 2
	v_readlane_b32 s39, v247, 3
	v_readlane_b32 s40, v247, 4
	v_readlane_b32 s41, v247, 5
	s_cmp_lg_u64 s[22:23], 0
	v_mul_u32_u24_e32 v3, 0x84, v4
	v_lshlrev_b32_e32 v5, 2, v60
	v_readlane_b32 s6, v247, 60
	s_movk_i32 s0, 0x580
	v_readlane_b32 s42, v247, 6
	v_lshl_add_u64 v[0:1], s[36:37], 0, v[10:11]
	v_add3_u32 v61, v2, v3, v5
	v_lshl_add_u64 v[2:3], s[38:39], 0, v[10:11]
	v_lshl_add_u64 v[6:7], s[40:41], 0, v[10:11]
	v_lshlrev_b32_e32 v10, 1, v4
	v_readlane_b32 s7, v247, 61
	s_cselect_b64 s[10:11], -1, 0
	v_cmp_gt_i32_e64 s[4:5], s0, v162
	v_or_b32_e32 v62, 8, v60
	v_or_b32_e32 v63, 16, v60
	v_or_b32_e32 v64, 24, v60
	v_lshl_add_u64 v[8:9], s[6:7], 0, v[10:11]
	v_lshl_add_u64 v[10:11], s[84:85], 0, v[10:11]
	v_mul_u32_u24_e32 v12, 0xb00, v60
	v_lshlrev_b32_e32 v5, 5, v162
	s_mov_b32 s3, 0x2e8ba2e9
	s_movk_i32 s38, 0xf500
	s_movk_i32 s39, 0x2c00
	v_cndmask_b32_e64 v65, 0, 1, s[10:11]
	s_movk_i32 s40, 0xffa8
	s_movk_i32 s41, 0x57f
	v_mov_b32_e32 v66, 0xb00000
	v_mov_b32_e32 v67, 13
	v_mov_b32_e32 v68, 2
	s_mov_b32 s42, 0
	v_readlane_b32 s43, v247, 7
	v_readlane_b32 s17, v247, 9
	v_readlane_b32 s18, v247, 10
	v_readlane_b32 s19, v247, 11
	v_readlane_b32 s20, v247, 12
	v_readlane_b32 s21, v247, 13
	v_readlane_b32 s24, v247, 16
	v_readlane_b32 s25, v247, 17
	v_readlane_b32 s26, v247, 18
	v_readlane_b32 s27, v247, 19
	v_readlane_b32 s28, v247, 20
	v_readlane_b32 s29, v247, 21
	v_readlane_b32 s30, v247, 22
	v_readlane_b32 s31, v247, 23
	s_branch .LBB0_18

; __device__ __forceinline__ void transpose_matrix(const float* W, int K, int N, bf16_t* WT, int mode, LAS float* scr, int gw, int ngw, int lane, const float* gk = nullptr) {
;     ...
;     for (int it = gw; it < items; it += ngw) { const int kb = it / nblk, nb = it % nblk, n0 = 32 * nb;
; __global__ void __launch_bounds__(512, 2) fwd_kernel(Args a) {
;     ...
;         for (int l = 0; l < 4; ++l) {
;             transpose_matrix(a.f_wg + (size_t)l * DM * FF, DM, FF, Wgu + (size_t)l * NGU * DM, 1, scr, gw, NGW, lane, a.norm_ffn_g + l * DM);
;             transpose_matrix(a.f_wu + (size_t)l * DM * FF, DM, FF, Wgu + (size_t)l * NGU * DM, 2, scr, gw, NGW, lane, a.norm_ffn_g + l * DM);
;             transpose_matrix(a.f_wd + (size_t)l * FF * DM, FF, DM, Wd + (size_t)l * DM * FF, 0, scr, gw, NGW, lane);
.LBB0_18:
	s_lshr_b32 s98, s33, 2
	s_mul_i32 s98, s98, s42
	v_add_u32_e32 v162, s98, v255
	v_cmp_le_u32_e32 vcc, s33, v162
	v_subrev_u32_e32 v254, s33, v162
	s_nop 0
	v_cndmask_b32_e32 v162, v162, v254, vcc
	v_cmp_gt_i32_e32 vcc, 0x580, v162
	v_lshlrev_b32_e32 v5, 5, v162
	s_mov_b64 s[4:5], vcc
	s_and_saveexec_b64 s[14:15], s[4:5]
	s_cbranch_execz .LBB0_17
	s_lshl_b32 s0, s42, 10
	v_readlane_b32 s16, v247, 8
	s_lshl_b64 s[6:7], s[0:1], 2
	v_readlane_b32 s22, v247, 14
	s_mul_hi_u32 s69, s42, 0x2c0000
	s_mul_i32 s68, s42, 0x2c0000
	v_readlane_b32 s23, v247, 15
	s_add_u32 s72, s22, s6
	s_mul_hi_u32 s71, s42, 0xb00000
	s_mul_i32 s70, s42, 0xb00000
	s_addc_u32 s73, s23, s7
	v_lshl_add_u64 v[16:17], s[68:69], 2, v[0:1]
	v_mad_u64_u32 v[14:15], s[6:7], s42, v66, v[10:11]
	s_lshl_b32 s0, s33, 5
	s_mov_b64 s[36:37], 0
	v_mov_b32_e32 v18, v5
	v_mov_b32_e32 v20, v162
	v_readlane_b32 s17, v247, 9
	v_readlane_b32 s18, v247, 10
	v_readlane_b32 s19, v247, 11
	v_readlane_b32 s20, v247, 12
	v_readlane_b32 s21, v247, 13
	v_readlane_b32 s24, v247, 16
	v_readlane_b32 s25, v247, 17
	v_readlane_b32 s26, v247, 18
	v_readlane_b32 s27, v247, 19
	v_readlane_b32 s28, v247, 20
	v_readlane_b32 s29, v247, 21
	v_readlane_b32 s30, v247, 22
	v_readlane_b32 s31, v247, 23
	s_branch .LBB0_21

; __device__ __forceinline__ void transpose_matrix(const float* W, int K, int N, bf16_t* WT, int mode, LAS float* scr, int gw, int ngw, int lane, const float* gk = nullptr) {
;     ...
;     for (int it = gw; it < items; it += ngw) { const int kb = it / nblk, nb = it % nblk, n0 = 32 * nb;
;         const int orow = mode == 0 ? n0 : ((n0 / 128) * 256 + (n0 % 128) + (mode == 2 ? 128 : 0));
;         transpose_item(W, K, N, WT, 64 * kb, n0, orow, scr, lane, gk); }
; __global__ void __launch_bounds__(512, 2) fwd_kernel(Args a) {
;     ...
;         transpose_matrix(a.w_qkv, DM, NQKV, Wqkv, 0, scr, gw, NGW, lane, a.norm_mix_g + 1 * DM);
.LBB0_29:
	s_lshr_b32 s98, s33, 2
	v_add_u32_e32 v162, s98, v255
	v_cmp_le_u32_e32 vcc, s33, v162
	v_subrev_u32_e32 v254, s33, v162
	s_nop 0
	v_cndmask_b32_e32 v162, v162, v254, vcc
	s_movk_i32 s0, 0x600
	v_cmp_gt_i32_e32 vcc, s0, v162
	v_lshlrev_b32_e32 v2, 2, v168
	v_lshlrev_b32_e32 v0, 1, v4
	s_and_saveexec_b64 s[0:1], vcc
	s_cbranch_execz .LBB0_32
	v_readlane_b32 s16, v247, 8
	v_readlane_b32 s20, v247, 12
	v_mov_b32_e32 v3, 0
	v_readlane_b32 s36, v247, 26
	v_readlane_b32 s21, v247, 13
	s_add_u32 s4, s20, 0x1000
	v_readlane_b32 s38, v247, 28
	v_readlane_b32 s39, v247, 29
	v_mov_b32_e32 v1, v3
	s_addc_u32 s5, s21, 0
	v_lshl_add_u64 v[4:5], s[38:39], 0, v[2:3]
	v_lshl_add_u64 v[6:7], s[94:95], 0, v[0:1]
	v_lshlrev_b32_e32 v8, 5, v162
	s_lshl_b32 s3, s33, 5
	s_mov_b64 s[6:7], 0
	s_mov_b32 s10, 0x2aaaaaab
	s_movk_i32 s11, 0xf400
	s_movk_i32 s14, 0x3000
	s_movk_i32 s15, 0x5ff
	v_add_u32_e32 v1, 0x400, v13
	v_add_u32_e32 v3, 0x800, v13
	v_add_u32_e32 v9, 0xc00, v13
	v_add_u32_e32 v10, 0x1000, v13
	v_add_u32_e32 v11, 0x1400, v13
	v_add_u32_e32 v12, 0x1800, v13
	v_add_u32_e32 v14, 0x1c00, v13
	v_mov_b32_e32 v15, v162
	v_readlane_b32 s17, v247, 9
	v_readlane_b32 s18, v247, 10
	v_readlane_b32 s19, v247, 11
	v_readlane_b32 s22, v247, 14
	v_readlane_b32 s23, v247, 15
	v_readlane_b32 s24, v247, 16
	v_readlane_b32 s25, v247, 17
	v_readlane_b32 s26, v247, 18
	v_readlane_b32 s27, v247, 19
	v_readlane_b32 s28, v247, 20
	v_readlane_b32 s29, v247, 21
	v_readlane_b32 s30, v247, 22
	v_readlane_b32 s31, v247, 23
	v_readlane_b32 s37, v247, 27
	v_readlane_b32 s40, v247, 30
	v_readlane_b32 s41, v247, 31
	v_readlane_b32 s42, v247, 32
	v_readlane_b32 s43, v247, 33
	v_readlane_b32 s44, v247, 34
	v_readlane_b32 s45, v247, 35
	v_readlane_b32 s46, v247, 36
	v_readlane_b32 s47, v247, 37
	v_readlane_b32 s48, v247, 38
	v_readlane_b32 s49, v247, 39
	v_readlane_b32 s50, v247, 40
	v_readlane_b32 s51, v247, 41

; __device__ __forceinline__ void transpose_matrix(const float* W, int K, int N, bf16_t* WT, int mode, LAS float* scr, int gw, int ngw, int lane, const float* gk = nullptr) {
;     ...
;     for (int it = gw; it < items; it += ngw) { const int kb = it / nblk, nb = it % nblk, n0 = 32 * nb;
;         const int orow = mode == 0 ? n0 : ((n0 / 128) * 256 + (n0 % 128) + (mode == 2 ? 128 : 0));
;         transpose_item(W, K, N, WT, 64 * kb, n0, orow, scr, lane, gk); }
; __global__ void __launch_bounds__(512, 2) fwd_kernel(Args a) {
;     ...
;         transpose_matrix(a.w_o, DM, DM, Wo, 0, scr, gw, NGW, lane);
.LBB0_32:
	s_or_b64 exec, exec, s[0:1]
	s_lshr_b32 s98, s33, 1
	v_add_u32_e32 v162, s98, v255
	v_cmp_le_u32_e32 vcc, s33, v162
	v_subrev_u32_e32 v254, s33, v162
	s_nop 0
	v_cndmask_b32_e32 v162, v162, v254, vcc
	s_movk_i32 s0, 0x200
	v_cmp_gt_i32_e32 vcc, s0, v162
	s_and_saveexec_b64 s[4:5], vcc
	s_cbranch_execz .LBB0_35
	v_mov_b32_e32 v3, 0
	v_readlane_b32 s36, v247, 26
	v_readlane_b32 s0, v247, 62
	v_readlane_b32 s40, v247, 30
	v_readlane_b32 s41, v247, 31
	v_mov_b32_e32 v1, v3
	v_readlane_b32 s1, v247, 63
	v_lshl_add_u64 v[4:5], s[40:41], 0, v[2:3]
	s_lshl_b32 s3, s33, 5
	v_lshl_add_u64 v[6:7], s[0:1], 0, v[0:1]
	v_lshlrev_b32_e32 v1, 5, v162
	s_mov_b64 s[6:7], 0
	s_movk_i32 s10, 0x1ff
	v_add_u32_e32 v3, 0x400, v13
	v_add_u32_e32 v12, 0x800, v13
	v_add_u32_e32 v14, 0xc00, v13
	v_add_u32_e32 v15, 0x1000, v13
	v_add_u32_e32 v16, 0x1400, v13
	v_add_u32_e32 v17, 0x1800, v13
	v_add_u32_e32 v18, 0x1c00, v13
	v_mov_b32_e32 v19, v162
	v_readlane_b32 s37, v247, 27
	v_readlane_b32 s38, v247, 28
	v_readlane_b32 s39, v247, 29
	v_readlane_b32 s42, v247, 32
	v_readlane_b32 s43, v247, 33
	v_readlane_b32 s44, v247, 34
	v_readlane_b32 s45, v247, 35
	v_readlane_b32 s46, v247, 36
	v_readlane_b32 s47, v247, 37
	v_readlane_b32 s48, v247, 38
	v_readlane_b32 s49, v247, 39
	v_readlane_b32 s50, v247, 40
	v_readlane_b32 s51, v247, 41

; __global__ void __launch_bounds__(512, 2) fwd_kernel(Args a) {
;     ...
;         {   const int nblk = 2048 / 32, items = (DM / 64) * nblk;
;             for (int it = gw; it < items; it += NGW) { const int kb = it / nblk, nb = it % nblk, n0 = 32 * nb; const int half = n0 >= DM, j0 = n0 - half * DM;
;                 transpose_item(a.c_win, DM, 2048, Win, 64 * kb, n0, (j0 / 128) * 256 + (j0 % 128) + half * 128, scr, lane, a.norm_mix_g + 2 * DM); } }
.LBB0_35:
	s_or_b64 exec, exec, s[4:5]
	v_mov_b32_e32 v162, v255
	s_movk_i32 s0, 0x400
	v_cmp_gt_i32_e64 s[0:1], s0, v162
	s_and_saveexec_b64 s[4:5], s[0:1]
	s_cbranch_execz .LBB0_38
	v_readlane_b32 s16, v247, 8
	v_readlane_b32 s20, v247, 12
	v_readlane_b32 s17, v247, 9
	v_readlane_b32 s18, v247, 10
	v_readlane_b32 s19, v247, 11
	v_readlane_b32 s21, v247, 13
	v_readlane_b32 s22, v247, 14
	v_readlane_b32 s23, v247, 15
	v_readlane_b32 s24, v247, 16
	v_readlane_b32 s25, v247, 17
	v_readlane_b32 s26, v247, 18
	v_readlane_b32 s27, v247, 19
	v_readlane_b32 s28, v247, 20
	v_readlane_b32 s29, v247, 21
	v_readlane_b32 s30, v247, 22
	v_readlane_b32 s31, v247, 23
	s_add_u32 s6, s20, 0x2000
	s_addc_u32 s7, s21, 0
	v_mov_b32_e32 v3, 0
	v_readlane_b32 s16, v247, 42
	v_readlane_b32 s0, v247, 58
	v_readlane_b32 s17, v247, 43
	v_mov_b32_e32 v1, v3
	v_readlane_b32 s1, v247, 59
	v_lshl_add_u64 v[4:5], s[16:17], 0, v[2:3]
	s_lshl_b32 s3, s33, 5
	v_lshl_add_u64 v[6:7], s[0:1], 0, v[0:1]
	v_lshlrev_b32_e32 v1, 5, v162
	s_mov_b64 s[10:11], 0
	v_mov_b32_e32 v3, 0xfc00
	v_mov_b32_e32 v12, 0x80
	s_movk_i32 s14, 0x3ff
	v_mov_b32_e32 v14, 8
	v_add_u32_e32 v15, 0x400, v13
	v_add_u32_e32 v16, 0x800, v13
	v_add_u32_e32 v17, 0xc00, v13
	v_add_u32_e32 v18, 0x1000, v13
	v_add_u32_e32 v19, 0x1400, v13
	v_add_u32_e32 v20, 0x1800, v13
	v_add_u32_e32 v21, 0x1c00, v13
	v_mov_b32_e32 v22, v162
	v_readlane_b32 s18, v247, 44
	v_readlane_b32 s19, v247, 45
	v_readlane_b32 s20, v247, 46
	v_readlane_b32 s21, v247, 47
	v_readlane_b32 s22, v247, 48
	v_readlane_b32 s23, v247, 49
	v_readlane_b32 s24, v247, 50
	v_readlane_b32 s25, v247, 51
	v_readlane_b32 s26, v247, 52
	v_readlane_b32 s27, v247, 53
	v_readlane_b32 s28, v247, 54
	v_readlane_b32 s29, v247, 55
	v_readlane_b32 s30, v247, 56
	v_readlane_b32 s31, v247, 57

; __device__ __forceinline__ void transpose_matrix(const float* W, int K, int N, bf16_t* WT, int mode, LAS float* scr, int gw, int ngw, int lane, const float* gk = nullptr) {
;     ...
;     for (int it = gw; it < items; it += ngw) { const int kb = it / nblk, nb = it % nblk, n0 = 32 * nb;
;         const int orow = mode == 0 ? n0 : ((n0 / 128) * 256 + (n0 % 128) + (mode == 2 ? 128 : 0));
;         transpose_item(W, K, N, WT, 64 * kb, n0, orow, scr, lane, gk); }
; __global__ void __launch_bounds__(512, 2) fwd_kernel(Args a) {
;     ...
;         transpose_matrix(a.c_wout, DM, DM, Wout, 0, scr, gw, NGW, lane);
.LBB0_38:
	s_or_b64 exec, exec, s[4:5]
	s_lshr_b32 s98, s33, 2
	s_mul_i32 s98, s98, 3
	v_add_u32_e32 v162, s98, v255
	v_cmp_le_u32_e32 vcc, s33, v162
	v_subrev_u32_e32 v254, s33, v162
	s_nop 0
	v_cndmask_b32_e32 v162, v162, v254, vcc
	v_cmp_gt_i32_e32 vcc, 0x200, v162
	s_and_saveexec_b64 s[0:1], vcc
	s_cbranch_execz .LBB0_41
	v_mov_b32_e32 v3, 0
	v_readlane_b32 s16, v247, 42
	v_readlane_b32 s28, v247, 54
	v_readlane_b32 s29, v247, 55
	v_mov_b32_e32 v1, v3
	v_lshl_add_u64 v[6:7], s[96:97], 0, v[0:1]
	v_lshl_add_u64 v[4:5], s[28:29], 0, v[2:3]
	v_lshlrev_b32_e32 v1, 5, v162
	s_lshl_b32 s3, s33, 5
	s_mov_b64 s[4:5], 0
	s_movk_i32 s6, 0x1ff
	v_add_u32_e32 v3, 0x400, v13
	v_add_u32_e32 v12, 0x800, v13
	v_add_u32_e32 v14, 0xc00, v13
	v_add_u32_e32 v15, 0x1000, v13
	v_add_u32_e32 v16, 0x1400, v13
	v_add_u32_e32 v17, 0x1800, v13
	v_add_u32_e32 v18, 0x1c00, v13
	v_mov_b32_e32 v19, v162
	v_readlane_b32 s17, v247, 43
	v_readlane_b32 s18, v247, 44
	v_readlane_b32 s19, v247, 45
	v_readlane_b32 s20, v247, 46
	v_readlane_b32 s21, v247, 47
	v_readlane_b32 s22, v247, 48
	v_readlane_b32 s23, v247, 49
	v_readlane_b32 s24, v247, 50
	v_readlane_b32 s25, v247, 51
	v_readlane_b32 s26, v247, 52
	v_readlane_b32 s27, v247, 53
	v_readlane_b32 s30, v247, 56
	v_readlane_b32 s31, v247, 57

; __device__ __forceinline__ void transpose_matrix(const float* W, int K, int N, bf16_t* WT, int mode, LAS float* scr, int gw, int ngw, int lane, const float* gk = nullptr) {
;     ...
;     for (int it = gw; it < items; it += ngw) { const int kb = it / nblk, nb = it % nblk, n0 = 32 * nb;
;         const int orow = mode == 0 ? n0 : ((n0 / 128) * 256 + (n0 % 128) + (mode == 2 ? 128 : 0));
;         transpose_item(W, K, N, WT, 64 * kb, n0, orow, scr, lane, gk); }
; __global__ void __launch_bounds__(512, 2) fwd_kernel(Args a) {
;     ...
;         for (int jg = 0; jg < 8; ++jg) transpose_matrix(a.pool_w + (size_t)jg * 256 * 256, 256, 256, Wp + (size_t)jg * 256 * 256, 0, scr, gw, NGW, lane);
.LBB0_43:
	s_lshr_b32 s99, s33, 4
	s_mul_i32 s98, s99, 3
	s_cmp_lt_u32 s14, 4
	s_cselect_b32 s99, 0, s99
	s_mul_i32 s99, s99, 7
	s_add_i32 s98, s98, s99
	s_lshr_b32 s99, s33, 6
	s_mul_i32 s99, s99, s14
	s_add_i32 s98, s98, s99
	v_add_u32_e32 v162, s98, v255
	v_cmp_le_u32_e32 vcc, s33, v162
	v_subrev_u32_e32 v254, s33, v162
	s_nop 0
	v_cndmask_b32_e32 v162, v162, v254, vcc
	v_cmp_gt_i32_e32 vcc, 32, v162
	v_lshlrev_b32_e32 v12, 5, v162
	s_and_saveexec_b64 s[6:7], vcc
	s_cbranch_execz .LBB0_42
	s_lshl_b32 s4, s14, 16
	v_lshl_add_u64 v[2:3], s[4:5], 2, v[4:5]
	s_lshl_b32 s4, s14, 17
	v_lshl_add_u64 v[6:7], v[0:1], 0, s[4:5]
	s_mov_b64 s[10:11], 0
	v_mov_b32_e32 v21, v12
	v_mov_b32_e32 v22, v162

; __device__ __forceinline__ unsigned pk2(float lo, float hi) { f32x2_t v = {lo, hi}; bf16x2_t b = __builtin_convertvector(v, bf16x2_t); return __builtin_bit_cast(unsigned, b); }
; __device__ __forceinline__ void init_row(const float* src, float* hrow, bf16_t* hb, float* ssp, float* ssm, int lane) {
;     float s = 0.f;
; #pragma unroll
;     for (int j = 0; j < 4; ++j) { const f32x4 v = *((const f32x4*)src + lane + 64 * j); s += (v.x * v.x + v.y * v.y) + (v.z * v.z + v.w * v.w);
;         u32x2 o; o.x = pk2(v.x, v.y); o.y = pk2(v.z, v.w); *((u32x2*)hb + lane + 64 * j) = o; }
;     s = wave_sum(s); if (lane < 16) ssp[lane] = lane == 0 ? s : 0.f;
;     if (ssm) ssm[lane] = lane == 0 ? s : 0.f;
; __global__ void __launch_bounds__(512, 2) fwd_kernel(Args a) {
;     ...
; #pragma unroll 2
;         for (int r = gw; r < MROWS; r += NGW) { const int b = r / LSEQ, p = r % LSEQ;
;             const float* src = p < NMETA ? a.meta + (size_t)p * DM : a.x + ((size_t)b * SEQ + (p - NMETA)) * DM;
;             init_row(src, H + (size_t)r * DM, Y + (size_t)r * DM, SSP + (size_t)r * 16, r < NMETA ? SSM + r * 64 : nullptr, lane); }
.LBB0_46:
	v_mov_b32_e32 v162, v255
	s_mov_b32 s0, 0x8020
	v_cmp_gt_i32_e32 vcc, s0, v162
	s_and_saveexec_b64 s[6:7], vcc
	s_cbranch_execz .LBB0_57
	v_mov_b32_e32 v1, 0
	v_lshlrev_b32_e32 v0, 3, v164
	v_lshl_add_u64 v[2:3], s[80:81], 0, v[0:1]
	v_mbcnt_lo_u32_b32 v0, -1, 0
	v_mbcnt_hi_u32_b32 v0, -1, v0
	v_and_b32_e32 v4, 64, v0
	v_add_u32_e32 v4, 64, v4
	v_xor_b32_e32 v5, 1, v0
	v_cmp_lt_i32_e32 vcc, v5, v4
	v_cmp_eq_u32_e64 s[4:5], 0, v164
	v_lshlrev_b32_e32 v6, 6, v162
	v_cndmask_b32_e32 v5, v0, v5, vcc
	v_lshlrev_b32_e32 v18, 2, v5
	v_xor_b32_e32 v5, 2, v0
	v_cmp_lt_i32_e32 vcc, v5, v4
	s_lshl_b32 s3, s33, 6
	s_mov_b64 s[10:11], 0
	v_cndmask_b32_e32 v5, v0, v5, vcc
	v_lshlrev_b32_e32 v19, 2, v5
	v_xor_b32_e32 v5, 4, v0
	v_cmp_lt_i32_e32 vcc, v5, v4
	s_mov_b32 s22, 0x7fe007ff
	v_lshlrev_b32_e32 v8, 4, v164
	v_cndmask_b32_e32 v5, v0, v5, vcc
	v_lshlrev_b32_e32 v20, 2, v5
	v_xor_b32_e32 v5, 8, v0
	v_cmp_lt_i32_e32 vcc, v5, v4
	v_mov_b32_e32 v9, v1
	s_mov_b32 s23, 0x801f
	v_cndmask_b32_e32 v5, v0, v5, vcc
	v_lshlrev_b32_e32 v21, 2, v5
	v_xor_b32_e32 v5, 16, v0
	v_cmp_lt_i32_e32 vcc, v5, v4
	v_mov_b32_e32 v10, v162
	s_nop 0
	v_cndmask_b32_e32 v5, v0, v5, vcc
	v_lshlrev_b32_e32 v22, 2, v5
	v_xor_b32_e32 v5, 32, v0
	v_cmp_lt_i32_e32 vcc, v5, v4
	s_nop 1
	v_cndmask_b32_e32 v0, v0, v5, vcc
	v_lshlrev_b32_e32 v23, 2, v0
	v_lshlrev_b32_e32 v0, 2, v164
	v_cmp_gt_u32_e32 vcc, 16, v164
	v_lshl_add_u64 v[4:5], s[82:83], 0, v[0:1]
	s_branch .LBB0_49
